# conv_weights tr_item loops: the 16 serialized load-pair round trips per pass batched (all 16 loads issued, then counted waits + LDS writes)
# baseline (speedup 1.0000x reference)
; #define LAS __attribute__((address_space(3)))
; #define LDS_WAIT() asm volatile("s_waitcnt lgkmcnt(0)" ::: "memory")
; __device__ __forceinline__ void tr_item(const float* W, int Nsrc, int k0, int j0, const float* kscale, bf16_t* WT, int Kdst, int R0, LAS float* scr, int lane) {
;     if (j0 >= 0) {
; #pragma unroll 8
;         for (int i = 0; i < 32; ++i) { const int kk = 2 * i + (lane >> 5); float v = W[(size_t)(k0 + kk) * Nsrc + j0 + (lane & 31)]; if (kscale) v *= kscale[k0 + kk]; scr[kk * 33 + (lane & 31)] = v; }
;     } else {
; #pragma unroll 8
;         for (int i = 0; i < 32; ++i) { const int kk = 2 * i + (lane >> 5); scr[kk * 33 + (lane & 31)] = 0.f; }
;     }
;     LDS_WAIT();
.LBB0_241:
	s_lshl_b32 s37, s8, 1
	s_lshl_b32 s30, s3, 1
	v_or_b32_e32 v40, s37, v2
	v_or_b32_e32 v0, s30, v3
	v_add_u32_e32 v38, s2, v40
	v_add_u32_e32 v36, s7, v0
	v_ashrrev_i32_e32 v39, 31, v38
	v_ashrrev_i32_e32 v37, 31, v36
	v_lshlrev_b64 v[38:39], 12, v[38:39]
	v_lshlrev_b64 v[36:37], 12, v[36:37]
	v_lshl_add_u64 v[38:39], v[34:35], 0, v[38:39]
	v_lshl_add_u64 v[36:37], v[34:35], 0, v[36:37]
	global_load_dword v41, v[38:39], off
	global_load_dword v42, v[36:37], off
	s_add_i32 s39, s37, 4
	s_add_i32 s38, s30, 4
	v_or_b32_e32 v40, s39, v2
	v_or_b32_e32 v0, s38, v3
	v_add_u32_e32 v38, s2, v40
	v_add_u32_e32 v36, s7, v0
	v_ashrrev_i32_e32 v39, 31, v38
	v_ashrrev_i32_e32 v37, 31, v36
	v_lshlrev_b64 v[38:39], 12, v[38:39]
	v_lshlrev_b64 v[36:37], 12, v[36:37]
	v_lshl_add_u64 v[38:39], v[34:35], 0, v[38:39]
	v_lshl_add_u64 v[36:37], v[34:35], 0, v[36:37]
	global_load_dword v240, v[38:39], off
	global_load_dword v241, v[36:37], off
	s_add_i32 s39, s37, 8
	s_add_i32 s38, s30, 8
	v_or_b32_e32 v40, s39, v2
	v_or_b32_e32 v0, s38, v3
	v_add_u32_e32 v38, s2, v40
	v_add_u32_e32 v36, s7, v0
	v_ashrrev_i32_e32 v39, 31, v38
	v_ashrrev_i32_e32 v37, 31, v36
	v_lshlrev_b64 v[38:39], 12, v[38:39]
	v_lshlrev_b64 v[36:37], 12, v[36:37]
	v_lshl_add_u64 v[38:39], v[34:35], 0, v[38:39]
	v_lshl_add_u64 v[36:37], v[34:35], 0, v[36:37]
	global_load_dword v242, v[38:39], off
	global_load_dword v243, v[36:37], off
	s_add_i32 s39, s37, 12
	s_add_i32 s38, s30, 12
	v_or_b32_e32 v40, s39, v2
	v_or_b32_e32 v0, s38, v3
	v_add_u32_e32 v38, s2, v40
	v_add_u32_e32 v36, s7, v0
	v_ashrrev_i32_e32 v39, 31, v38
	v_ashrrev_i32_e32 v37, 31, v36
	v_lshlrev_b64 v[38:39], 12, v[38:39]
	v_lshlrev_b64 v[36:37], 12, v[36:37]
	v_lshl_add_u64 v[38:39], v[34:35], 0, v[38:39]
	v_lshl_add_u64 v[36:37], v[34:35], 0, v[36:37]
	global_load_dword v244, v[38:39], off
	global_load_dword v245, v[36:37], off
	s_add_i32 s39, s37, 16
	s_add_i32 s38, s30, 16
	v_or_b32_e32 v40, s39, v2
	v_or_b32_e32 v0, s38, v3
	v_add_u32_e32 v38, s2, v40
	v_add_u32_e32 v36, s7, v0
	v_ashrrev_i32_e32 v39, 31, v38
	v_ashrrev_i32_e32 v37, 31, v36
	v_lshlrev_b64 v[38:39], 12, v[38:39]
	v_lshlrev_b64 v[36:37], 12, v[36:37]
	v_lshl_add_u64 v[38:39], v[34:35], 0, v[38:39]
	v_lshl_add_u64 v[36:37], v[34:35], 0, v[36:37]
	global_load_dword v246, v[38:39], off
	global_load_dword v247, v[36:37], off
	s_add_i32 s39, s37, 20
	s_add_i32 s38, s30, 20
	v_or_b32_e32 v40, s39, v2
	v_or_b32_e32 v0, s38, v3
	v_add_u32_e32 v38, s2, v40
	v_add_u32_e32 v36, s7, v0
	v_ashrrev_i32_e32 v39, 31, v38
	v_ashrrev_i32_e32 v37, 31, v36
	v_lshlrev_b64 v[38:39], 12, v[38:39]
	v_lshlrev_b64 v[36:37], 12, v[36:37]
	v_lshl_add_u64 v[38:39], v[34:35], 0, v[38:39]
	v_lshl_add_u64 v[36:37], v[34:35], 0, v[36:37]
	global_load_dword v248, v[38:39], off
	global_load_dword v249, v[36:37], off
	s_add_i32 s39, s37, 24
	s_add_i32 s38, s30, 24
	v_or_b32_e32 v40, s39, v2
	v_or_b32_e32 v0, s38, v3
	v_add_u32_e32 v38, s2, v40
	v_add_u32_e32 v36, s7, v0
	v_ashrrev_i32_e32 v39, 31, v38
	v_ashrrev_i32_e32 v37, 31, v36
	v_lshlrev_b64 v[38:39], 12, v[38:39]
	v_lshlrev_b64 v[36:37], 12, v[36:37]
	v_lshl_add_u64 v[38:39], v[34:35], 0, v[38:39]
	v_lshl_add_u64 v[36:37], v[34:35], 0, v[36:37]
	global_load_dword v250, v[38:39], off
	global_load_dword v251, v[36:37], off
	s_add_i32 s39, s37, 28
	s_add_i32 s38, s30, 28
	v_or_b32_e32 v40, s39, v2
	v_or_b32_e32 v0, s38, v3
	v_add_u32_e32 v38, s2, v40
	v_add_u32_e32 v36, s7, v0
	v_ashrrev_i32_e32 v39, 31, v38
	v_ashrrev_i32_e32 v37, 31, v36
	v_lshlrev_b64 v[38:39], 12, v[38:39]
	v_lshlrev_b64 v[36:37], 12, v[36:37]
	v_lshl_add_u64 v[38:39], v[34:35], 0, v[38:39]
	v_lshl_add_u64 v[36:37], v[34:35], 0, v[36:37]
	global_load_dword v252, v[38:39], off
	global_load_dword v253, v[36:37], off
	s_add_i32 s8, s8, 16
	s_add_i32 s3, s3, 16
	s_add_i32 s9, s9, -16
	v_or_b32_e32 v40, s37, v2
	v_or_b32_e32 v0, s30, v3
	v_mad_u64_u32 v[36:37], s[38:39], v40, s75, v[6:7]
	v_mad_u64_u32 v[38:39], s[38:39], v0, s75, v[6:7]
	s_waitcnt vmcnt(14)
	ds_write_b32 v36, v41
	ds_write_b32 v38, v42
	s_add_i32 s39, s37, 4
	s_add_i32 s38, s30, 4
	v_or_b32_e32 v40, s39, v2
	v_or_b32_e32 v0, s38, v3
	v_mad_u64_u32 v[36:37], s[38:39], v40, s75, v[6:7]
	v_mad_u64_u32 v[38:39], s[38:39], v0, s75, v[6:7]
	s_waitcnt vmcnt(12)
	ds_write_b32 v36, v240
	ds_write_b32 v38, v241
	s_add_i32 s39, s37, 8
	s_add_i32 s38, s30, 8
	v_or_b32_e32 v40, s39, v2
	v_or_b32_e32 v0, s38, v3
	v_mad_u64_u32 v[36:37], s[38:39], v40, s75, v[6:7]
	v_mad_u64_u32 v[38:39], s[38:39], v0, s75, v[6:7]
	s_waitcnt vmcnt(10)
	ds_write_b32 v36, v242
	ds_write_b32 v38, v243
	s_add_i32 s39, s37, 12
	s_add_i32 s38, s30, 12
	v_or_b32_e32 v40, s39, v2
	v_or_b32_e32 v0, s38, v3
	v_mad_u64_u32 v[36:37], s[38:39], v40, s75, v[6:7]
	v_mad_u64_u32 v[38:39], s[38:39], v0, s75, v[6:7]
	s_waitcnt vmcnt(8)
	ds_write_b32 v36, v244
	ds_write_b32 v38, v245
	s_add_i32 s39, s37, 16
	s_add_i32 s38, s30, 16
	v_or_b32_e32 v40, s39, v2
	v_or_b32_e32 v0, s38, v3
	v_mad_u64_u32 v[36:37], s[38:39], v40, s75, v[6:7]
	v_mad_u64_u32 v[38:39], s[38:39], v0, s75, v[6:7]
	s_waitcnt vmcnt(6)
	ds_write_b32 v36, v246
	ds_write_b32 v38, v247
	s_add_i32 s39, s37, 20
	s_add_i32 s38, s30, 20
	v_or_b32_e32 v40, s39, v2
	v_or_b32_e32 v0, s38, v3
	v_mad_u64_u32 v[36:37], s[38:39], v40, s75, v[6:7]
	v_mad_u64_u32 v[38:39], s[38:39], v0, s75, v[6:7]
	s_waitcnt vmcnt(4)
	ds_write_b32 v36, v248
	ds_write_b32 v38, v249
	s_add_i32 s39, s37, 24
	s_add_i32 s38, s30, 24
	v_or_b32_e32 v40, s39, v2
	v_or_b32_e32 v0, s38, v3
	v_mad_u64_u32 v[36:37], s[38:39], v40, s75, v[6:7]
	v_mad_u64_u32 v[38:39], s[38:39], v0, s75, v[6:7]
	s_waitcnt vmcnt(2)
	ds_write_b32 v36, v250
	ds_write_b32 v38, v251
	s_add_i32 s39, s37, 28
	s_add_i32 s38, s30, 28
	v_or_b32_e32 v40, s39, v2
	v_or_b32_e32 v0, s38, v3
	v_mad_u64_u32 v[36:37], s[38:39], v40, s75, v[6:7]
	v_mad_u64_u32 v[38:39], s[38:39], v0, s75, v[6:7]
	s_waitcnt vmcnt(0)
	ds_write_b32 v36, v252
	ds_write_b32 v38, v253
	s_cmp_lg_u32 s9, 0
	s_cbranch_scc1 .LBB0_241
; __device__ __forceinline__ unsigned cvt_pk_bf16(float lo, float hi) { unsigned r; asm volatile("v_cvt_pk_bf16_f32 %0, %1, %2" : "=v"(r) : "v"(lo), "v"(hi)); return r; }
; #define LAS __attribute__((address_space(3)))
; #define LDS_WAIT() asm volatile("s_waitcnt lgkmcnt(0)" ::: "memory")
; __device__ __forceinline__ void tr_item(const float* W, int Nsrc, int k0, int j0, const float* kscale, bf16_t* WT, int Kdst, int R0, LAS float* scr, int lane) {
;     ...
;     const int c = lane & 7;
; #pragma unroll
;     for (int j = 0; j < 4; ++j) { const int n = (lane >> 3) + 8 * j; const LAS float* s = scr + (8 * c) * 33 + n;
;         u32x4 o; o.x = cvt_pk_bf16(s[0 * 33], s[1 * 33]); o.y = cvt_pk_bf16(s[2 * 33], s[3 * 33]); o.z = cvt_pk_bf16(s[4 * 33], s[5 * 33]); o.w = cvt_pk_bf16(s[6 * 33], s[7 * 33]);
;         *(u32x4*)(WT + (size_t)(R0 + n) * Kdst + k0 + 8 * c) = o; }
;     LDS_WAIT();
	s_waitcnt lgkmcnt(0)
	ds_read2_b32 v[34:35], v7 offset1:33
	s_waitcnt lgkmcnt(0)
	v_cvt_pk_bf16_f32 v34, v34, v35
	ds_read2_b32 v[36:37], v7 offset0:66 offset1:99
	v_or_b32_e32 v0, s6, v5
	s_mov_b32 s3, s31
	s_waitcnt lgkmcnt(0)
	v_cvt_pk_bf16_f32 v35, v36, v37
	ds_read2_b32 v[36:37], v7 offset0:132 offset1:165
	v_mul_u32_u24_e32 v0, 0xb00, v0
	v_lshl_add_u64 v[38:39], s[2:3], 1, v[8:9]
	s_waitcnt lgkmcnt(0)
	v_cvt_pk_bf16_f32 v36, v36, v37
	ds_read2_b32 v[40:41], v7 offset0:198 offset1:231
	v_lshlrev_b32_e32 v0, 1, v0
	s_waitcnt lgkmcnt(0)
	v_cvt_pk_bf16_f32 v37, v40, v41
	v_lshl_add_u64 v[40:41], v[38:39], 0, v[0:1]
	global_store_dwordx4 v[40:41], v[34:37], off
	ds_read2_b32 v[34:35], v7 offset0:8 offset1:41
	v_or_b32_e32 v0, s6, v56
	s_waitcnt lgkmcnt(0)
	v_cvt_pk_bf16_f32 v34, v34, v35
	ds_read2_b32 v[36:37], v7 offset0:74 offset1:107
	s_waitcnt lgkmcnt(0)
	v_cvt_pk_bf16_f32 v35, v36, v37
	ds_read2_b32 v[36:37], v7 offset0:140 offset1:173
	v_mul_u32_u24_e32 v0, 0xb00, v0
	s_waitcnt lgkmcnt(0)
	v_cvt_pk_bf16_f32 v36, v36, v37
	ds_read2_b32 v[40:41], v7 offset0:206 offset1:239
	v_lshlrev_b32_e32 v0, 1, v0
	s_waitcnt lgkmcnt(0)
	v_cvt_pk_bf16_f32 v37, v40, v41
	v_lshl_add_u64 v[40:41], v[38:39], 0, v[0:1]
	global_store_dwordx4 v[40:41], v[34:37], off
	ds_read2_b32 v[34:35], v7 offset0:16 offset1:49
	v_or_b32_e32 v0, s6, v57
	s_waitcnt lgkmcnt(0)
	v_cvt_pk_bf16_f32 v34, v34, v35
	ds_read2_b32 v[36:37], v7 offset0:82 offset1:115
	s_waitcnt lgkmcnt(0)
	v_cvt_pk_bf16_f32 v35, v36, v37
	ds_read2_b32 v[36:37], v7 offset0:148 offset1:181
	v_mul_u32_u24_e32 v0, 0xb00, v0
	s_waitcnt lgkmcnt(0)
	v_cvt_pk_bf16_f32 v36, v36, v37
	ds_read2_b32 v[40:41], v7 offset0:214 offset1:247
	v_lshlrev_b32_e32 v0, 1, v0
	s_waitcnt lgkmcnt(0)
	v_cvt_pk_bf16_f32 v37, v40, v41
	v_lshl_add_u64 v[40:41], v[38:39], 0, v[0:1]
	v_or_b32_e32 v0, s6, v58
	global_store_dwordx4 v[40:41], v[34:37], off
	ds_read2_b32 v[34:35], v7 offset0:24 offset1:57
	v_mul_u32_u24_e32 v0, 0xb00, v0
	s_waitcnt lgkmcnt(0)
	v_cvt_pk_bf16_f32 v34, v34, v35
	ds_read2_b32 v[36:37], v7 offset0:90 offset1:123
	v_lshlrev_b32_e32 v0, 1, v0
	s_waitcnt lgkmcnt(0)
	v_cvt_pk_bf16_f32 v35, v36, v37
	ds_read2_b32 v[36:37], v7 offset0:156 offset1:189
	v_lshl_add_u64 v[38:39], v[38:39], 0, v[0:1]
	s_waitcnt lgkmcnt(0)
	v_cvt_pk_bf16_f32 v36, v36, v37
	ds_read2_b32 v[40:41], v7 offset0:222 offset1:255
	s_waitcnt lgkmcnt(0)
	v_cvt_pk_bf16_f32 v37, v40, v41
	global_store_dwordx4 v[38:39], v[34:37], off
	s_waitcnt lgkmcnt(0)
	s_mov_b64 s[2:3], 0

; #define LAS __attribute__((address_space(3)))
; #define LDS_WAIT() asm volatile("s_waitcnt lgkmcnt(0)" ::: "memory")
; __device__ __forceinline__ void tr_item(const float* W, int Nsrc, int k0, int j0, const float* kscale, bf16_t* WT, int Kdst, int R0, LAS float* scr, int lane) {
;     if (j0 >= 0) {
; #pragma unroll 8
;         for (int i = 0; i < 32; ++i) { const int kk = 2 * i + (lane >> 5); float v = W[(size_t)(k0 + kk) * Nsrc + j0 + (lane & 31)]; if (kscale) v *= kscale[k0 + kk]; scr[kk * 33 + (lane & 31)] = v; }
;     } else {
; #pragma unroll 8
;         for (int i = 0; i < 32; ++i) { const int kk = 2 * i + (lane >> 5); scr[kk * 33 + (lane & 31)] = 0.f; }
;     }
;     LDS_WAIT();
.LBB0_245:
	s_lshl_b32 s37, s3, 1
	s_lshl_b32 s30, s8, 1
	v_or_b32_e32 v40, s37, v2
	v_or_b32_e32 v0, s30, v3
	v_add_u32_e32 v36, s6, v40
	v_add_u32_e32 v38, s7, v0
	v_mad_u64_u32 v[36:37], s[38:39], v36, s40, v[34:35]
	v_mad_u64_u32 v[38:39], s[38:39], v38, s40, v[34:35]
	global_load_dword v41, v[36:37], off
	global_load_dword v42, v[38:39], off
	s_add_i32 s39, s37, 4
	s_add_i32 s38, s30, 4
	v_or_b32_e32 v40, s39, v2
	v_or_b32_e32 v0, s38, v3
	v_add_u32_e32 v36, s6, v40
	v_add_u32_e32 v38, s7, v0
	v_mad_u64_u32 v[36:37], s[38:39], v36, s40, v[34:35]
	v_mad_u64_u32 v[38:39], s[38:39], v38, s40, v[34:35]
	global_load_dword v240, v[36:37], off
	global_load_dword v241, v[38:39], off
	s_add_i32 s39, s37, 8
	s_add_i32 s38, s30, 8
	v_or_b32_e32 v40, s39, v2
	v_or_b32_e32 v0, s38, v3
	v_add_u32_e32 v36, s6, v40
	v_add_u32_e32 v38, s7, v0
	v_mad_u64_u32 v[36:37], s[38:39], v36, s40, v[34:35]
	v_mad_u64_u32 v[38:39], s[38:39], v38, s40, v[34:35]
	global_load_dword v242, v[36:37], off
	global_load_dword v243, v[38:39], off
	s_add_i32 s39, s37, 12
	s_add_i32 s38, s30, 12
	v_or_b32_e32 v40, s39, v2
	v_or_b32_e32 v0, s38, v3
	v_add_u32_e32 v36, s6, v40
	v_add_u32_e32 v38, s7, v0
	v_mad_u64_u32 v[36:37], s[38:39], v36, s40, v[34:35]
	v_mad_u64_u32 v[38:39], s[38:39], v38, s40, v[34:35]
	global_load_dword v244, v[36:37], off
	global_load_dword v245, v[38:39], off
	s_add_i32 s39, s37, 16
	s_add_i32 s38, s30, 16
	v_or_b32_e32 v40, s39, v2
	v_or_b32_e32 v0, s38, v3
	v_add_u32_e32 v36, s6, v40
	v_add_u32_e32 v38, s7, v0
	v_mad_u64_u32 v[36:37], s[38:39], v36, s40, v[34:35]
	v_mad_u64_u32 v[38:39], s[38:39], v38, s40, v[34:35]
	global_load_dword v246, v[36:37], off
	global_load_dword v247, v[38:39], off
	s_add_i32 s39, s37, 20
	s_add_i32 s38, s30, 20
	v_or_b32_e32 v40, s39, v2
	v_or_b32_e32 v0, s38, v3
	v_add_u32_e32 v36, s6, v40
	v_add_u32_e32 v38, s7, v0
	v_mad_u64_u32 v[36:37], s[38:39], v36, s40, v[34:35]
	v_mad_u64_u32 v[38:39], s[38:39], v38, s40, v[34:35]
	global_load_dword v248, v[36:37], off
	global_load_dword v249, v[38:39], off
	s_add_i32 s39, s37, 24
	s_add_i32 s38, s30, 24
	v_or_b32_e32 v40, s39, v2
	v_or_b32_e32 v0, s38, v3
	v_add_u32_e32 v36, s6, v40
	v_add_u32_e32 v38, s7, v0
	v_mad_u64_u32 v[36:37], s[38:39], v36, s40, v[34:35]
	v_mad_u64_u32 v[38:39], s[38:39], v38, s40, v[34:35]
	global_load_dword v250, v[36:37], off
	global_load_dword v251, v[38:39], off
	s_add_i32 s39, s37, 28
	s_add_i32 s38, s30, 28
	v_or_b32_e32 v40, s39, v2
	v_or_b32_e32 v0, s38, v3
	v_add_u32_e32 v36, s6, v40
	v_add_u32_e32 v38, s7, v0
	v_mad_u64_u32 v[36:37], s[38:39], v36, s40, v[34:35]
	v_mad_u64_u32 v[38:39], s[38:39], v38, s40, v[34:35]
	global_load_dword v252, v[36:37], off
	global_load_dword v253, v[38:39], off
	s_add_i32 s3, s3, 16
	s_add_i32 s8, s8, 16
	s_add_i32 s9, s9, -16
	v_or_b32_e32 v40, s37, v2
	v_or_b32_e32 v0, s30, v3
	v_mad_u64_u32 v[36:37], s[38:39], v40, s75, v[6:7]
	v_mad_u64_u32 v[38:39], s[38:39], v0, s75, v[6:7]
	s_waitcnt vmcnt(14)
	ds_write_b32 v36, v41
	ds_write_b32 v38, v42
	s_add_i32 s39, s37, 4
	s_add_i32 s38, s30, 4
	v_or_b32_e32 v40, s39, v2
	v_or_b32_e32 v0, s38, v3
	v_mad_u64_u32 v[36:37], s[38:39], v40, s75, v[6:7]
	v_mad_u64_u32 v[38:39], s[38:39], v0, s75, v[6:7]
	s_waitcnt vmcnt(12)
	ds_write_b32 v36, v240
	ds_write_b32 v38, v241
	s_add_i32 s39, s37, 8
	s_add_i32 s38, s30, 8
	v_or_b32_e32 v40, s39, v2
	v_or_b32_e32 v0, s38, v3
	v_mad_u64_u32 v[36:37], s[38:39], v40, s75, v[6:7]
	v_mad_u64_u32 v[38:39], s[38:39], v0, s75, v[6:7]
	s_waitcnt vmcnt(10)
	ds_write_b32 v36, v242
	ds_write_b32 v38, v243
	s_add_i32 s39, s37, 12
	s_add_i32 s38, s30, 12
	v_or_b32_e32 v40, s39, v2
	v_or_b32_e32 v0, s38, v3
	v_mad_u64_u32 v[36:37], s[38:39], v40, s75, v[6:7]
	v_mad_u64_u32 v[38:39], s[38:39], v0, s75, v[6:7]
	s_waitcnt vmcnt(8)
	ds_write_b32 v36, v244
	ds_write_b32 v38, v245
	s_add_i32 s39, s37, 16
	s_add_i32 s38, s30, 16
	v_or_b32_e32 v40, s39, v2
	v_or_b32_e32 v0, s38, v3
	v_mad_u64_u32 v[36:37], s[38:39], v40, s75, v[6:7]
	v_mad_u64_u32 v[38:39], s[38:39], v0, s75, v[6:7]
	s_waitcnt vmcnt(6)
	ds_write_b32 v36, v246
	ds_write_b32 v38, v247
	s_add_i32 s39, s37, 20
	s_add_i32 s38, s30, 20
	v_or_b32_e32 v40, s39, v2
	v_or_b32_e32 v0, s38, v3
	v_mad_u64_u32 v[36:37], s[38:39], v40, s75, v[6:7]
	v_mad_u64_u32 v[38:39], s[38:39], v0, s75, v[6:7]
	s_waitcnt vmcnt(4)
	ds_write_b32 v36, v248
	ds_write_b32 v38, v249
	s_add_i32 s39, s37, 24
	s_add_i32 s38, s30, 24
	v_or_b32_e32 v40, s39, v2
	v_or_b32_e32 v0, s38, v3
	v_mad_u64_u32 v[36:37], s[38:39], v40, s75, v[6:7]
	v_mad_u64_u32 v[38:39], s[38:39], v0, s75, v[6:7]
	s_waitcnt vmcnt(2)
	ds_write_b32 v36, v250
	ds_write_b32 v38, v251
	s_add_i32 s39, s37, 28
	s_add_i32 s38, s30, 28
	v_or_b32_e32 v40, s39, v2
	v_or_b32_e32 v0, s38, v3
	v_mad_u64_u32 v[36:37], s[38:39], v40, s75, v[6:7]
	v_mad_u64_u32 v[38:39], s[38:39], v0, s75, v[6:7]
	s_waitcnt vmcnt(0)
	ds_write_b32 v36, v252
	ds_write_b32 v38, v253
	s_cmp_lg_u32 s9, 0
	s_cbranch_scc1 .LBB0_245
; __device__ __forceinline__ unsigned cvt_pk_bf16(float lo, float hi) { unsigned r; asm volatile("v_cvt_pk_bf16_f32 %0, %1, %2" : "=v"(r) : "v"(lo), "v"(hi)); return r; }
; #define LAS __attribute__((address_space(3)))
; #define LDS_WAIT() asm volatile("s_waitcnt lgkmcnt(0)" ::: "memory")
; __device__ __forceinline__ void tr_item(const float* W, int Nsrc, int k0, int j0, const float* kscale, bf16_t* WT, int Kdst, int R0, LAS float* scr, int lane) {
;     ...
;     const int c = lane & 7;
; #pragma unroll
;     for (int j = 0; j < 4; ++j) { const int n = (lane >> 3) + 8 * j; const LAS float* s = scr + (8 * c) * 33 + n;
;         u32x4 o; o.x = cvt_pk_bf16(s[0 * 33], s[1 * 33]); o.y = cvt_pk_bf16(s[2 * 33], s[3 * 33]); o.z = cvt_pk_bf16(s[4 * 33], s[5 * 33]); o.w = cvt_pk_bf16(s[6 * 33], s[7 * 33]);
;         *(u32x4*)(WT + (size_t)(R0 + n) * Kdst + k0 + 8 * c) = o; }
;     LDS_WAIT();
	s_waitcnt lgkmcnt(0)
	ds_read2_b32 v[34:35], v7 offset1:33
	s_and_b32 s3, 0xffff, s6
	s_waitcnt lgkmcnt(0)
	v_cvt_pk_bf16_f32 v34, v34, v35
	ds_read2_b32 v[36:37], v7 offset0:66 offset1:99
	s_lshl_b32 s30, s3, 1
	s_waitcnt lgkmcnt(0)
	v_cvt_pk_bf16_f32 v35, v36, v37
	ds_read2_b32 v[36:37], v7 offset0:132 offset1:165
	v_or_b32_e32 v0, s2, v5
	v_lshl_add_u64 v[38:39], v[10:11], 0, s[30:31]
	s_waitcnt lgkmcnt(0)
	v_cvt_pk_bf16_f32 v36, v36, v37
	ds_read2_b32 v[40:41], v7 offset0:198 offset1:231
	v_lshlrev_b32_e32 v0, 11, v0
	s_waitcnt lgkmcnt(0)
	v_cvt_pk_bf16_f32 v37, v40, v41
	v_lshl_add_u64 v[40:41], v[38:39], 0, v[0:1]
	global_store_dwordx4 v[40:41], v[34:37], off
	ds_read2_b32 v[34:35], v7 offset0:8 offset1:41
	v_or_b32_e32 v0, s2, v56
	s_waitcnt lgkmcnt(0)
	v_cvt_pk_bf16_f32 v34, v34, v35
	ds_read2_b32 v[36:37], v7 offset0:74 offset1:107
	s_waitcnt lgkmcnt(0)
	v_cvt_pk_bf16_f32 v35, v36, v37
	ds_read2_b32 v[36:37], v7 offset0:140 offset1:173
	s_waitcnt lgkmcnt(0)
	v_cvt_pk_bf16_f32 v36, v36, v37
	ds_read2_b32 v[40:41], v7 offset0:206 offset1:239
	v_lshlrev_b32_e32 v0, 11, v0
	s_waitcnt lgkmcnt(0)
	v_cvt_pk_bf16_f32 v37, v40, v41
	v_lshl_add_u64 v[40:41], v[38:39], 0, v[0:1]
	global_store_dwordx4 v[40:41], v[34:37], off
	ds_read2_b32 v[34:35], v7 offset0:16 offset1:49
	v_or_b32_e32 v0, s2, v57
	s_waitcnt lgkmcnt(0)
	v_cvt_pk_bf16_f32 v34, v34, v35
	ds_read2_b32 v[36:37], v7 offset0:82 offset1:115
	s_waitcnt lgkmcnt(0)
	v_cvt_pk_bf16_f32 v35, v36, v37
	ds_read2_b32 v[36:37], v7 offset0:148 offset1:181
	s_waitcnt lgkmcnt(0)
	v_cvt_pk_bf16_f32 v36, v36, v37
	ds_read2_b32 v[40:41], v7 offset0:214 offset1:247
	v_lshlrev_b32_e32 v0, 11, v0
	s_waitcnt lgkmcnt(0)
	v_cvt_pk_bf16_f32 v37, v40, v41
	v_lshl_add_u64 v[40:41], v[38:39], 0, v[0:1]
	global_store_dwordx4 v[40:41], v[34:37], off
	ds_read2_b32 v[34:35], v7 offset0:24 offset1:57
	v_or_b32_e32 v0, s2, v58
	s_waitcnt lgkmcnt(0)
	v_cvt_pk_bf16_f32 v34, v34, v35
	ds_read2_b32 v[36:37], v7 offset0:90 offset1:123
	v_lshlrev_b32_e32 v0, 11, v0
	s_waitcnt lgkmcnt(0)
	v_cvt_pk_bf16_f32 v35, v36, v37
	ds_read2_b32 v[36:37], v7 offset0:156 offset1:189
	v_lshl_add_u64 v[38:39], v[38:39], 0, v[0:1]
	s_waitcnt lgkmcnt(0)
	v_cvt_pk_bf16_f32 v36, v36, v37
	ds_read2_b32 v[40:41], v7 offset0:222 offset1:255
	s_waitcnt lgkmcnt(0)
	v_cvt_pk_bf16_f32 v37, v40, v41
	global_store_dwordx4 v[38:39], v[34:37], off
	s_waitcnt lgkmcnt(0)

; #define LAS __attribute__((address_space(3)))
; #define LDS_WAIT() asm volatile("s_waitcnt lgkmcnt(0)" ::: "memory")
; __device__ __forceinline__ void tr_item(const float* W, int Nsrc, int k0, int j0, const float* kscale, bf16_t* WT, int Kdst, int R0, LAS float* scr, int lane) {
;     if (j0 >= 0) {
; #pragma unroll 8
;         for (int i = 0; i < 32; ++i) { const int kk = 2 * i + (lane >> 5); float v = W[(size_t)(k0 + kk) * Nsrc + j0 + (lane & 31)]; if (kscale) v *= kscale[k0 + kk]; scr[kk * 33 + (lane & 31)] = v; }
;     } else {
; #pragma unroll 8
;         for (int i = 0; i < 32; ++i) { const int kk = 2 * i + (lane >> 5); scr[kk * 33 + (lane & 31)] = 0.f; }
;     }
;     LDS_WAIT();
.LBB0_250:
	s_lshl_b32 s37, s8, 1
	s_lshl_b32 s30, s3, 1
	v_or_b32_e32 v40, s37, v2
	v_or_b32_e32 v0, s30, v3
	v_add_u32_e32 v38, s2, v40
	v_add_u32_e32 v36, s7, v0
	v_ashrrev_i32_e32 v39, 31, v38
	v_ashrrev_i32_e32 v37, 31, v36
	v_lshlrev_b64 v[38:39], 12, v[38:39]
	v_lshlrev_b64 v[36:37], 12, v[36:37]
	v_lshl_add_u64 v[38:39], v[34:35], 0, v[38:39]
	v_lshl_add_u64 v[36:37], v[34:35], 0, v[36:37]
	global_load_dword v41, v[38:39], off
	global_load_dword v42, v[36:37], off
	s_add_i32 s39, s37, 4
	s_add_i32 s38, s30, 4
	v_or_b32_e32 v40, s39, v2
	v_or_b32_e32 v0, s38, v3
	v_add_u32_e32 v38, s2, v40
	v_add_u32_e32 v36, s7, v0
	v_ashrrev_i32_e32 v39, 31, v38
	v_ashrrev_i32_e32 v37, 31, v36
	v_lshlrev_b64 v[38:39], 12, v[38:39]
	v_lshlrev_b64 v[36:37], 12, v[36:37]
	v_lshl_add_u64 v[38:39], v[34:35], 0, v[38:39]
	v_lshl_add_u64 v[36:37], v[34:35], 0, v[36:37]
	global_load_dword v240, v[38:39], off
	global_load_dword v241, v[36:37], off
	s_add_i32 s39, s37, 8
	s_add_i32 s38, s30, 8
	v_or_b32_e32 v40, s39, v2
	v_or_b32_e32 v0, s38, v3
	v_add_u32_e32 v38, s2, v40
	v_add_u32_e32 v36, s7, v0
	v_ashrrev_i32_e32 v39, 31, v38
	v_ashrrev_i32_e32 v37, 31, v36
	v_lshlrev_b64 v[38:39], 12, v[38:39]
	v_lshlrev_b64 v[36:37], 12, v[36:37]
	v_lshl_add_u64 v[38:39], v[34:35], 0, v[38:39]
	v_lshl_add_u64 v[36:37], v[34:35], 0, v[36:37]
	global_load_dword v242, v[38:39], off
	global_load_dword v243, v[36:37], off
	s_add_i32 s39, s37, 12
	s_add_i32 s38, s30, 12
	v_or_b32_e32 v40, s39, v2
	v_or_b32_e32 v0, s38, v3
	v_add_u32_e32 v38, s2, v40
	v_add_u32_e32 v36, s7, v0
	v_ashrrev_i32_e32 v39, 31, v38
	v_ashrrev_i32_e32 v37, 31, v36
	v_lshlrev_b64 v[38:39], 12, v[38:39]
	v_lshlrev_b64 v[36:37], 12, v[36:37]
	v_lshl_add_u64 v[38:39], v[34:35], 0, v[38:39]
	v_lshl_add_u64 v[36:37], v[34:35], 0, v[36:37]
	global_load_dword v244, v[38:39], off
	global_load_dword v245, v[36:37], off
	s_add_i32 s39, s37, 16
	s_add_i32 s38, s30, 16
	v_or_b32_e32 v40, s39, v2
	v_or_b32_e32 v0, s38, v3
	v_add_u32_e32 v38, s2, v40
	v_add_u32_e32 v36, s7, v0
	v_ashrrev_i32_e32 v39, 31, v38
	v_ashrrev_i32_e32 v37, 31, v36
	v_lshlrev_b64 v[38:39], 12, v[38:39]
	v_lshlrev_b64 v[36:37], 12, v[36:37]
	v_lshl_add_u64 v[38:39], v[34:35], 0, v[38:39]
	v_lshl_add_u64 v[36:37], v[34:35], 0, v[36:37]
	global_load_dword v246, v[38:39], off
	global_load_dword v247, v[36:37], off
	s_add_i32 s39, s37, 20
	s_add_i32 s38, s30, 20
	v_or_b32_e32 v40, s39, v2
	v_or_b32_e32 v0, s38, v3
	v_add_u32_e32 v38, s2, v40
	v_add_u32_e32 v36, s7, v0
	v_ashrrev_i32_e32 v39, 31, v38
	v_ashrrev_i32_e32 v37, 31, v36
	v_lshlrev_b64 v[38:39], 12, v[38:39]
	v_lshlrev_b64 v[36:37], 12, v[36:37]
	v_lshl_add_u64 v[38:39], v[34:35], 0, v[38:39]
	v_lshl_add_u64 v[36:37], v[34:35], 0, v[36:37]
	global_load_dword v248, v[38:39], off
	global_load_dword v249, v[36:37], off
	s_add_i32 s39, s37, 24
	s_add_i32 s38, s30, 24
	v_or_b32_e32 v40, s39, v2
	v_or_b32_e32 v0, s38, v3
	v_add_u32_e32 v38, s2, v40
	v_add_u32_e32 v36, s7, v0
	v_ashrrev_i32_e32 v39, 31, v38
	v_ashrrev_i32_e32 v37, 31, v36
	v_lshlrev_b64 v[38:39], 12, v[38:39]
	v_lshlrev_b64 v[36:37], 12, v[36:37]
	v_lshl_add_u64 v[38:39], v[34:35], 0, v[38:39]
	v_lshl_add_u64 v[36:37], v[34:35], 0, v[36:37]
	global_load_dword v250, v[38:39], off
	global_load_dword v251, v[36:37], off
	s_add_i32 s39, s37, 28
	s_add_i32 s38, s30, 28
	v_or_b32_e32 v40, s39, v2
	v_or_b32_e32 v0, s38, v3
	v_add_u32_e32 v38, s2, v40
	v_add_u32_e32 v36, s7, v0
	v_ashrrev_i32_e32 v39, 31, v38
	v_ashrrev_i32_e32 v37, 31, v36
	v_lshlrev_b64 v[38:39], 12, v[38:39]
	v_lshlrev_b64 v[36:37], 12, v[36:37]
	v_lshl_add_u64 v[38:39], v[34:35], 0, v[38:39]
	v_lshl_add_u64 v[36:37], v[34:35], 0, v[36:37]
	global_load_dword v252, v[38:39], off
	global_load_dword v253, v[36:37], off
	s_add_i32 s8, s8, 16
	s_add_i32 s3, s3, 16
	s_add_i32 s9, s9, -16
	v_or_b32_e32 v40, s37, v2
	v_or_b32_e32 v0, s30, v3
	v_mad_u64_u32 v[36:37], s[38:39], v40, s75, v[6:7]
	v_mad_u64_u32 v[38:39], s[38:39], v0, s75, v[6:7]
	s_waitcnt vmcnt(14)
	ds_write_b32 v36, v41
	ds_write_b32 v38, v42
	s_add_i32 s39, s37, 4
	s_add_i32 s38, s30, 4
	v_or_b32_e32 v40, s39, v2
	v_or_b32_e32 v0, s38, v3
	v_mad_u64_u32 v[36:37], s[38:39], v40, s75, v[6:7]
	v_mad_u64_u32 v[38:39], s[38:39], v0, s75, v[6:7]
	s_waitcnt vmcnt(12)
	ds_write_b32 v36, v240
	ds_write_b32 v38, v241
	s_add_i32 s39, s37, 8
	s_add_i32 s38, s30, 8
	v_or_b32_e32 v40, s39, v2
	v_or_b32_e32 v0, s38, v3
	v_mad_u64_u32 v[36:37], s[38:39], v40, s75, v[6:7]
	v_mad_u64_u32 v[38:39], s[38:39], v0, s75, v[6:7]
	s_waitcnt vmcnt(10)
	ds_write_b32 v36, v242
	ds_write_b32 v38, v243
	s_add_i32 s39, s37, 12
	s_add_i32 s38, s30, 12
	v_or_b32_e32 v40, s39, v2
	v_or_b32_e32 v0, s38, v3
	v_mad_u64_u32 v[36:37], s[38:39], v40, s75, v[6:7]
	v_mad_u64_u32 v[38:39], s[38:39], v0, s75, v[6:7]
	s_waitcnt vmcnt(8)
	ds_write_b32 v36, v244
	ds_write_b32 v38, v245
	s_add_i32 s39, s37, 16
	s_add_i32 s38, s30, 16
	v_or_b32_e32 v40, s39, v2
	v_or_b32_e32 v0, s38, v3
	v_mad_u64_u32 v[36:37], s[38:39], v40, s75, v[6:7]
	v_mad_u64_u32 v[38:39], s[38:39], v0, s75, v[6:7]
	s_waitcnt vmcnt(6)
	ds_write_b32 v36, v246
	ds_write_b32 v38, v247
	s_add_i32 s39, s37, 20
	s_add_i32 s38, s30, 20
	v_or_b32_e32 v40, s39, v2
	v_or_b32_e32 v0, s38, v3
	v_mad_u64_u32 v[36:37], s[38:39], v40, s75, v[6:7]
	v_mad_u64_u32 v[38:39], s[38:39], v0, s75, v[6:7]
	s_waitcnt vmcnt(4)
	ds_write_b32 v36, v248
	ds_write_b32 v38, v249
	s_add_i32 s39, s37, 24
	s_add_i32 s38, s30, 24
	v_or_b32_e32 v40, s39, v2
	v_or_b32_e32 v0, s38, v3
	v_mad_u64_u32 v[36:37], s[38:39], v40, s75, v[6:7]
	v_mad_u64_u32 v[38:39], s[38:39], v0, s75, v[6:7]
	s_waitcnt vmcnt(2)
	ds_write_b32 v36, v250
	ds_write_b32 v38, v251
	s_add_i32 s39, s37, 28
	s_add_i32 s38, s30, 28
	v_or_b32_e32 v40, s39, v2
	v_or_b32_e32 v0, s38, v3
	v_mad_u64_u32 v[36:37], s[38:39], v40, s75, v[6:7]
	v_mad_u64_u32 v[38:39], s[38:39], v0, s75, v[6:7]
	s_waitcnt vmcnt(0)
	ds_write_b32 v36, v252
	ds_write_b32 v38, v253
	s_cmp_lg_u32 s9, 0
	s_cbranch_scc1 .LBB0_250
; __device__ __forceinline__ unsigned cvt_pk_bf16(float lo, float hi) { unsigned r; asm volatile("v_cvt_pk_bf16_f32 %0, %1, %2" : "=v"(r) : "v"(lo), "v"(hi)); return r; }
; #define LAS __attribute__((address_space(3)))
; #define LDS_WAIT() asm volatile("s_waitcnt lgkmcnt(0)" ::: "memory")
; __device__ __forceinline__ void tr_item(const float* W, int Nsrc, int k0, int j0, const float* kscale, bf16_t* WT, int Kdst, int R0, LAS float* scr, int lane) {
;     ...
;     const int c = lane & 7;
; #pragma unroll
;     for (int j = 0; j < 4; ++j) { const int n = (lane >> 3) + 8 * j; const LAS float* s = scr + (8 * c) * 33 + n;
;         u32x4 o; o.x = cvt_pk_bf16(s[0 * 33], s[1 * 33]); o.y = cvt_pk_bf16(s[2 * 33], s[3 * 33]); o.z = cvt_pk_bf16(s[4 * 33], s[5 * 33]); o.w = cvt_pk_bf16(s[6 * 33], s[7 * 33]);
;         *(u32x4*)(WT + (size_t)(R0 + n) * Kdst + k0 + 8 * c) = o; }
;     LDS_WAIT();
	s_waitcnt lgkmcnt(0)
	ds_read2_b32 v[34:35], v7 offset1:33
	s_waitcnt lgkmcnt(0)
	v_cvt_pk_bf16_f32 v34, v34, v35
	ds_read2_b32 v[36:37], v7 offset0:66 offset1:99
	s_mov_b32 s3, s31
	s_waitcnt lgkmcnt(0)
	v_cvt_pk_bf16_f32 v35, v36, v37
	ds_read2_b32 v[36:37], v7 offset0:132 offset1:165
	v_or_b32_e32 v0, s6, v5
	v_lshl_add_u64 v[38:39], s[2:3], 1, v[12:13]
	s_waitcnt lgkmcnt(0)
	v_cvt_pk_bf16_f32 v36, v36, v37
	ds_read2_b32 v[40:41], v7 offset0:198 offset1:231
	v_lshlrev_b32_e32 v0, 11, v0
	s_waitcnt lgkmcnt(0)
	v_cvt_pk_bf16_f32 v37, v40, v41
	v_lshl_add_u64 v[40:41], v[38:39], 0, v[0:1]
	global_store_dwordx4 v[40:41], v[34:37], off
	ds_read2_b32 v[34:35], v7 offset0:8 offset1:41
	v_or_b32_e32 v0, s6, v56
	s_waitcnt lgkmcnt(0)
	v_cvt_pk_bf16_f32 v34, v34, v35
	ds_read2_b32 v[36:37], v7 offset0:74 offset1:107
	s_waitcnt lgkmcnt(0)
	v_cvt_pk_bf16_f32 v35, v36, v37
	ds_read2_b32 v[36:37], v7 offset0:140 offset1:173
	s_waitcnt lgkmcnt(0)
	v_cvt_pk_bf16_f32 v36, v36, v37
	ds_read2_b32 v[40:41], v7 offset0:206 offset1:239
	v_lshlrev_b32_e32 v0, 11, v0
	s_waitcnt lgkmcnt(0)
	v_cvt_pk_bf16_f32 v37, v40, v41
	v_lshl_add_u64 v[40:41], v[38:39], 0, v[0:1]
	global_store_dwordx4 v[40:41], v[34:37], off
	ds_read2_b32 v[34:35], v7 offset0:16 offset1:49
	v_or_b32_e32 v0, s6, v57
	s_waitcnt lgkmcnt(0)
	v_cvt_pk_bf16_f32 v34, v34, v35
	ds_read2_b32 v[36:37], v7 offset0:82 offset1:115
	s_waitcnt lgkmcnt(0)
	v_cvt_pk_bf16_f32 v35, v36, v37
	ds_read2_b32 v[36:37], v7 offset0:148 offset1:181
	s_waitcnt lgkmcnt(0)
	v_cvt_pk_bf16_f32 v36, v36, v37
	ds_read2_b32 v[40:41], v7 offset0:214 offset1:247
	v_lshlrev_b32_e32 v0, 11, v0
	s_waitcnt lgkmcnt(0)
	v_cvt_pk_bf16_f32 v37, v40, v41
	v_lshl_add_u64 v[40:41], v[38:39], 0, v[0:1]
	global_store_dwordx4 v[40:41], v[34:37], off
	ds_read2_b32 v[34:35], v7 offset0:24 offset1:57
	v_or_b32_e32 v0, s6, v58
	s_waitcnt lgkmcnt(0)
	v_cvt_pk_bf16_f32 v34, v34, v35
	ds_read2_b32 v[36:37], v7 offset0:90 offset1:123
	v_lshlrev_b32_e32 v0, 11, v0
	s_waitcnt lgkmcnt(0)
	v_cvt_pk_bf16_f32 v35, v36, v37
	ds_read2_b32 v[36:37], v7 offset0:156 offset1:189
	v_lshl_add_u64 v[38:39], v[38:39], 0, v[0:1]
	s_waitcnt lgkmcnt(0)
	v_cvt_pk_bf16_f32 v36, v36, v37
	ds_read2_b32 v[40:41], v7 offset0:222 offset1:255
	s_waitcnt lgkmcnt(0)
	v_cvt_pk_bf16_f32 v37, v40, v41
	global_store_dwordx4 v[38:39], v[34:37], off
	s_waitcnt lgkmcnt(0)

; #define LAS __attribute__((address_space(3)))
; #define LDS_WAIT() asm volatile("s_waitcnt lgkmcnt(0)" ::: "memory")
; __device__ __forceinline__ void tr_item(const float* W, int Nsrc, int k0, int j0, const float* kscale, bf16_t* WT, int Kdst, int R0, LAS float* scr, int lane) {
;     if (j0 >= 0) {
; #pragma unroll 8
;         for (int i = 0; i < 32; ++i) { const int kk = 2 * i + (lane >> 5); float v = W[(size_t)(k0 + kk) * Nsrc + j0 + (lane & 31)]; if (kscale) v *= kscale[k0 + kk]; scr[kk * 33 + (lane & 31)] = v; }
;     } else {
; #pragma unroll 8
;         for (int i = 0; i < 32; ++i) { const int kk = 2 * i + (lane >> 5); scr[kk * 33 + (lane & 31)] = 0.f; }
;     }
;     LDS_WAIT();
.LBB0_255:
	s_lshl_b32 s37, s8, 1
	s_lshl_b32 s30, s3, 1
	v_or_b32_e32 v40, s37, v2
	v_or_b32_e32 v0, s30, v3
	v_add_u32_e32 v38, s2, v40
	v_add_u32_e32 v36, s7, v0
	v_ashrrev_i32_e32 v39, 31, v38
	v_ashrrev_i32_e32 v37, 31, v36
	v_lshlrev_b64 v[38:39], 12, v[38:39]
	v_lshlrev_b64 v[36:37], 12, v[36:37]
	v_lshl_add_u64 v[38:39], v[34:35], 0, v[38:39]
	v_lshl_add_u64 v[36:37], v[34:35], 0, v[36:37]
	global_load_dword v41, v[38:39], off
	global_load_dword v42, v[36:37], off
	s_add_i32 s39, s37, 4
	s_add_i32 s38, s30, 4
	v_or_b32_e32 v40, s39, v2
	v_or_b32_e32 v0, s38, v3
	v_add_u32_e32 v38, s2, v40
	v_add_u32_e32 v36, s7, v0
	v_ashrrev_i32_e32 v39, 31, v38
	v_ashrrev_i32_e32 v37, 31, v36
	v_lshlrev_b64 v[38:39], 12, v[38:39]
	v_lshlrev_b64 v[36:37], 12, v[36:37]
	v_lshl_add_u64 v[38:39], v[34:35], 0, v[38:39]
	v_lshl_add_u64 v[36:37], v[34:35], 0, v[36:37]
	global_load_dword v240, v[38:39], off
	global_load_dword v241, v[36:37], off
	s_add_i32 s39, s37, 8
	s_add_i32 s38, s30, 8
	v_or_b32_e32 v40, s39, v2
	v_or_b32_e32 v0, s38, v3
	v_add_u32_e32 v38, s2, v40
	v_add_u32_e32 v36, s7, v0
	v_ashrrev_i32_e32 v39, 31, v38
	v_ashrrev_i32_e32 v37, 31, v36
	v_lshlrev_b64 v[38:39], 12, v[38:39]
	v_lshlrev_b64 v[36:37], 12, v[36:37]
	v_lshl_add_u64 v[38:39], v[34:35], 0, v[38:39]
	v_lshl_add_u64 v[36:37], v[34:35], 0, v[36:37]
	global_load_dword v242, v[38:39], off
	global_load_dword v243, v[36:37], off
	s_add_i32 s39, s37, 12
	s_add_i32 s38, s30, 12
	v_or_b32_e32 v40, s39, v2
	v_or_b32_e32 v0, s38, v3
	v_add_u32_e32 v38, s2, v40
	v_add_u32_e32 v36, s7, v0
	v_ashrrev_i32_e32 v39, 31, v38
	v_ashrrev_i32_e32 v37, 31, v36
	v_lshlrev_b64 v[38:39], 12, v[38:39]
	v_lshlrev_b64 v[36:37], 12, v[36:37]
	v_lshl_add_u64 v[38:39], v[34:35], 0, v[38:39]
	v_lshl_add_u64 v[36:37], v[34:35], 0, v[36:37]
	global_load_dword v244, v[38:39], off
	global_load_dword v245, v[36:37], off
	s_add_i32 s39, s37, 16
	s_add_i32 s38, s30, 16
	v_or_b32_e32 v40, s39, v2
	v_or_b32_e32 v0, s38, v3
	v_add_u32_e32 v38, s2, v40
	v_add_u32_e32 v36, s7, v0
	v_ashrrev_i32_e32 v39, 31, v38
	v_ashrrev_i32_e32 v37, 31, v36
	v_lshlrev_b64 v[38:39], 12, v[38:39]
	v_lshlrev_b64 v[36:37], 12, v[36:37]
	v_lshl_add_u64 v[38:39], v[34:35], 0, v[38:39]
	v_lshl_add_u64 v[36:37], v[34:35], 0, v[36:37]
	global_load_dword v246, v[38:39], off
	global_load_dword v247, v[36:37], off
	s_add_i32 s39, s37, 20
	s_add_i32 s38, s30, 20
	v_or_b32_e32 v40, s39, v2
	v_or_b32_e32 v0, s38, v3
	v_add_u32_e32 v38, s2, v40
	v_add_u32_e32 v36, s7, v0
	v_ashrrev_i32_e32 v39, 31, v38
	v_ashrrev_i32_e32 v37, 31, v36
	v_lshlrev_b64 v[38:39], 12, v[38:39]
	v_lshlrev_b64 v[36:37], 12, v[36:37]
	v_lshl_add_u64 v[38:39], v[34:35], 0, v[38:39]
	v_lshl_add_u64 v[36:37], v[34:35], 0, v[36:37]
	global_load_dword v248, v[38:39], off
	global_load_dword v249, v[36:37], off
	s_add_i32 s39, s37, 24
	s_add_i32 s38, s30, 24
	v_or_b32_e32 v40, s39, v2
	v_or_b32_e32 v0, s38, v3
	v_add_u32_e32 v38, s2, v40
	v_add_u32_e32 v36, s7, v0
	v_ashrrev_i32_e32 v39, 31, v38
	v_ashrrev_i32_e32 v37, 31, v36
	v_lshlrev_b64 v[38:39], 12, v[38:39]
	v_lshlrev_b64 v[36:37], 12, v[36:37]
	v_lshl_add_u64 v[38:39], v[34:35], 0, v[38:39]
	v_lshl_add_u64 v[36:37], v[34:35], 0, v[36:37]
	global_load_dword v250, v[38:39], off
	global_load_dword v251, v[36:37], off
	s_add_i32 s39, s37, 28
	s_add_i32 s38, s30, 28
	v_or_b32_e32 v40, s39, v2
	v_or_b32_e32 v0, s38, v3
	v_add_u32_e32 v38, s2, v40
	v_add_u32_e32 v36, s7, v0
	v_ashrrev_i32_e32 v39, 31, v38
	v_ashrrev_i32_e32 v37, 31, v36
	v_lshlrev_b64 v[38:39], 12, v[38:39]
	v_lshlrev_b64 v[36:37], 12, v[36:37]
	v_lshl_add_u64 v[38:39], v[34:35], 0, v[38:39]
	v_lshl_add_u64 v[36:37], v[34:35], 0, v[36:37]
	global_load_dword v252, v[38:39], off
	global_load_dword v253, v[36:37], off
	s_add_i32 s8, s8, 16
	s_add_i32 s3, s3, 16
	s_add_i32 s9, s9, -16
	v_or_b32_e32 v40, s37, v2
	v_or_b32_e32 v0, s30, v3
	v_mad_u64_u32 v[36:37], s[38:39], v40, s75, v[6:7]
	v_mad_u64_u32 v[38:39], s[38:39], v0, s75, v[6:7]
	s_waitcnt vmcnt(14)
	ds_write_b32 v36, v41
	ds_write_b32 v38, v42
	s_add_i32 s39, s37, 4
	s_add_i32 s38, s30, 4
	v_or_b32_e32 v40, s39, v2
	v_or_b32_e32 v0, s38, v3
	v_mad_u64_u32 v[36:37], s[38:39], v40, s75, v[6:7]
	v_mad_u64_u32 v[38:39], s[38:39], v0, s75, v[6:7]
	s_waitcnt vmcnt(12)
	ds_write_b32 v36, v240
	ds_write_b32 v38, v241
	s_add_i32 s39, s37, 8
	s_add_i32 s38, s30, 8
	v_or_b32_e32 v40, s39, v2
	v_or_b32_e32 v0, s38, v3
	v_mad_u64_u32 v[36:37], s[38:39], v40, s75, v[6:7]
	v_mad_u64_u32 v[38:39], s[38:39], v0, s75, v[6:7]
	s_waitcnt vmcnt(10)
	ds_write_b32 v36, v242
	ds_write_b32 v38, v243
	s_add_i32 s39, s37, 12
	s_add_i32 s38, s30, 12
	v_or_b32_e32 v40, s39, v2
	v_or_b32_e32 v0, s38, v3
	v_mad_u64_u32 v[36:37], s[38:39], v40, s75, v[6:7]
	v_mad_u64_u32 v[38:39], s[38:39], v0, s75, v[6:7]
	s_waitcnt vmcnt(8)
	ds_write_b32 v36, v244
	ds_write_b32 v38, v245
	s_add_i32 s39, s37, 16
	s_add_i32 s38, s30, 16
	v_or_b32_e32 v40, s39, v2
	v_or_b32_e32 v0, s38, v3
	v_mad_u64_u32 v[36:37], s[38:39], v40, s75, v[6:7]
	v_mad_u64_u32 v[38:39], s[38:39], v0, s75, v[6:7]
	s_waitcnt vmcnt(6)
	ds_write_b32 v36, v246
	ds_write_b32 v38, v247
	s_add_i32 s39, s37, 20
	s_add_i32 s38, s30, 20
	v_or_b32_e32 v40, s39, v2
	v_or_b32_e32 v0, s38, v3
	v_mad_u64_u32 v[36:37], s[38:39], v40, s75, v[6:7]
	v_mad_u64_u32 v[38:39], s[38:39], v0, s75, v[6:7]
	s_waitcnt vmcnt(4)
	ds_write_b32 v36, v248
	ds_write_b32 v38, v249
	s_add_i32 s39, s37, 24
	s_add_i32 s38, s30, 24
	v_or_b32_e32 v40, s39, v2
	v_or_b32_e32 v0, s38, v3
	v_mad_u64_u32 v[36:37], s[38:39], v40, s75, v[6:7]
	v_mad_u64_u32 v[38:39], s[38:39], v0, s75, v[6:7]
	s_waitcnt vmcnt(2)
	ds_write_b32 v36, v250
	ds_write_b32 v38, v251
	s_add_i32 s39, s37, 28
	s_add_i32 s38, s30, 28
	v_or_b32_e32 v40, s39, v2
	v_or_b32_e32 v0, s38, v3
	v_mad_u64_u32 v[36:37], s[38:39], v40, s75, v[6:7]
	v_mad_u64_u32 v[38:39], s[38:39], v0, s75, v[6:7]
	s_waitcnt vmcnt(0)
	ds_write_b32 v36, v252
	ds_write_b32 v38, v253
	s_cmp_lg_u32 s9, 0
	s_cbranch_scc1 .LBB0_255
; __device__ __forceinline__ unsigned cvt_pk_bf16(float lo, float hi) { unsigned r; asm volatile("v_cvt_pk_bf16_f32 %0, %1, %2" : "=v"(r) : "v"(lo), "v"(hi)); return r; }
; #define LAS __attribute__((address_space(3)))
; #define LDS_WAIT() asm volatile("s_waitcnt lgkmcnt(0)" ::: "memory")
; __device__ __forceinline__ void tr_item(const float* W, int Nsrc, int k0, int j0, const float* kscale, bf16_t* WT, int Kdst, int R0, LAS float* scr, int lane) {
;     ...
;     const int c = lane & 7;
; #pragma unroll
;     for (int j = 0; j < 4; ++j) { const int n = (lane >> 3) + 8 * j; const LAS float* s = scr + (8 * c) * 33 + n;
;         u32x4 o; o.x = cvt_pk_bf16(s[0 * 33], s[1 * 33]); o.y = cvt_pk_bf16(s[2 * 33], s[3 * 33]); o.z = cvt_pk_bf16(s[4 * 33], s[5 * 33]); o.w = cvt_pk_bf16(s[6 * 33], s[7 * 33]);
;         *(u32x4*)(WT + (size_t)(R0 + n) * Kdst + k0 + 8 * c) = o; }
;     LDS_WAIT();
	s_waitcnt lgkmcnt(0)
	ds_read2_b32 v[34:35], v7 offset1:33
	s_waitcnt lgkmcnt(0)
	v_cvt_pk_bf16_f32 v34, v34, v35
	ds_read2_b32 v[36:37], v7 offset0:66 offset1:99
	s_mov_b32 s3, s31
	s_waitcnt lgkmcnt(0)
	v_cvt_pk_bf16_f32 v35, v36, v37
	ds_read2_b32 v[36:37], v7 offset0:132 offset1:165
	v_or_b32_e32 v0, s6, v5
	v_lshl_add_u64 v[38:39], s[2:3], 1, v[14:15]
	s_waitcnt lgkmcnt(0)
	v_cvt_pk_bf16_f32 v36, v36, v37
	ds_read2_b32 v[40:41], v7 offset0:198 offset1:231
	v_lshlrev_b32_e32 v0, 11, v0
	s_waitcnt lgkmcnt(0)
	v_cvt_pk_bf16_f32 v37, v40, v41
	v_lshl_add_u64 v[40:41], v[38:39], 0, v[0:1]
	global_store_dwordx4 v[40:41], v[34:37], off
	ds_read2_b32 v[34:35], v7 offset0:8 offset1:41
	v_or_b32_e32 v0, s6, v56
	s_waitcnt lgkmcnt(0)
	v_cvt_pk_bf16_f32 v34, v34, v35
	ds_read2_b32 v[36:37], v7 offset0:74 offset1:107
	s_waitcnt lgkmcnt(0)
	v_cvt_pk_bf16_f32 v35, v36, v37
	ds_read2_b32 v[36:37], v7 offset0:140 offset1:173
	s_waitcnt lgkmcnt(0)
	v_cvt_pk_bf16_f32 v36, v36, v37
	ds_read2_b32 v[40:41], v7 offset0:206 offset1:239
	v_lshlrev_b32_e32 v0, 11, v0
	s_waitcnt lgkmcnt(0)
	v_cvt_pk_bf16_f32 v37, v40, v41
	v_lshl_add_u64 v[40:41], v[38:39], 0, v[0:1]
	global_store_dwordx4 v[40:41], v[34:37], off
	ds_read2_b32 v[34:35], v7 offset0:16 offset1:49
	v_or_b32_e32 v0, s6, v57
	s_waitcnt lgkmcnt(0)
	v_cvt_pk_bf16_f32 v34, v34, v35
	ds_read2_b32 v[36:37], v7 offset0:82 offset1:115
	s_waitcnt lgkmcnt(0)
	v_cvt_pk_bf16_f32 v35, v36, v37
	ds_read2_b32 v[36:37], v7 offset0:148 offset1:181
	s_waitcnt lgkmcnt(0)
	v_cvt_pk_bf16_f32 v36, v36, v37
	ds_read2_b32 v[40:41], v7 offset0:214 offset1:247
	v_lshlrev_b32_e32 v0, 11, v0
	s_waitcnt lgkmcnt(0)
	v_cvt_pk_bf16_f32 v37, v40, v41
	v_lshl_add_u64 v[40:41], v[38:39], 0, v[0:1]
	global_store_dwordx4 v[40:41], v[34:37], off
	ds_read2_b32 v[34:35], v7 offset0:24 offset1:57
	v_or_b32_e32 v0, s6, v58
	s_waitcnt lgkmcnt(0)
	v_cvt_pk_bf16_f32 v34, v34, v35
	ds_read2_b32 v[36:37], v7 offset0:90 offset1:123
	v_lshlrev_b32_e32 v0, 11, v0
	s_waitcnt lgkmcnt(0)
	v_cvt_pk_bf16_f32 v35, v36, v37
	ds_read2_b32 v[36:37], v7 offset0:156 offset1:189
	v_lshl_add_u64 v[38:39], v[38:39], 0, v[0:1]
	s_waitcnt lgkmcnt(0)
	v_cvt_pk_bf16_f32 v36, v36, v37
	ds_read2_b32 v[40:41], v7 offset0:222 offset1:255
	s_waitcnt lgkmcnt(0)
	v_cvt_pk_bf16_f32 v37, v40, v41
	global_store_dwordx4 v[38:39], v[34:37], off
	s_waitcnt lgkmcnt(0)

; #define LAS __attribute__((address_space(3)))
; #define LDS_WAIT() asm volatile("s_waitcnt lgkmcnt(0)" ::: "memory")
; __device__ __forceinline__ void tr_item(const float* W, int Nsrc, int k0, int j0, const float* kscale, bf16_t* WT, int Kdst, int R0, LAS float* scr, int lane) {
;     if (j0 >= 0) {
; #pragma unroll 8
;         for (int i = 0; i < 32; ++i) { const int kk = 2 * i + (lane >> 5); float v = W[(size_t)(k0 + kk) * Nsrc + j0 + (lane & 31)]; if (kscale) v *= kscale[k0 + kk]; scr[kk * 33 + (lane & 31)] = v; }
;     } else {
; #pragma unroll 8
;         for (int i = 0; i < 32; ++i) { const int kk = 2 * i + (lane >> 5); scr[kk * 33 + (lane & 31)] = 0.f; }
;     }
;     LDS_WAIT();
.LBB0_260:
	s_lshl_b32 s37, s8, 1
	s_lshl_b32 s30, s3, 1
	v_or_b32_e32 v40, s37, v2
	v_or_b32_e32 v0, s30, v3
	v_add_u32_e32 v38, s2, v40
	v_add_u32_e32 v36, s7, v0
	v_ashrrev_i32_e32 v39, 31, v38
	v_ashrrev_i32_e32 v37, 31, v36
	v_lshlrev_b64 v[38:39], 12, v[38:39]
	v_lshlrev_b64 v[36:37], 12, v[36:37]
	v_lshl_add_u64 v[38:39], v[34:35], 0, v[38:39]
	v_lshl_add_u64 v[36:37], v[34:35], 0, v[36:37]
	global_load_dword v41, v[38:39], off
	global_load_dword v42, v[36:37], off
	s_add_i32 s39, s37, 4
	s_add_i32 s38, s30, 4
	v_or_b32_e32 v40, s39, v2
	v_or_b32_e32 v0, s38, v3
	v_add_u32_e32 v38, s2, v40
	v_add_u32_e32 v36, s7, v0
	v_ashrrev_i32_e32 v39, 31, v38
	v_ashrrev_i32_e32 v37, 31, v36
	v_lshlrev_b64 v[38:39], 12, v[38:39]
	v_lshlrev_b64 v[36:37], 12, v[36:37]
	v_lshl_add_u64 v[38:39], v[34:35], 0, v[38:39]
	v_lshl_add_u64 v[36:37], v[34:35], 0, v[36:37]
	global_load_dword v240, v[38:39], off
	global_load_dword v241, v[36:37], off
	s_add_i32 s39, s37, 8
	s_add_i32 s38, s30, 8
	v_or_b32_e32 v40, s39, v2
	v_or_b32_e32 v0, s38, v3
	v_add_u32_e32 v38, s2, v40
	v_add_u32_e32 v36, s7, v0
	v_ashrrev_i32_e32 v39, 31, v38
	v_ashrrev_i32_e32 v37, 31, v36
	v_lshlrev_b64 v[38:39], 12, v[38:39]
	v_lshlrev_b64 v[36:37], 12, v[36:37]
	v_lshl_add_u64 v[38:39], v[34:35], 0, v[38:39]
	v_lshl_add_u64 v[36:37], v[34:35], 0, v[36:37]
	global_load_dword v242, v[38:39], off
	global_load_dword v243, v[36:37], off
	s_add_i32 s39, s37, 12
	s_add_i32 s38, s30, 12
	v_or_b32_e32 v40, s39, v2
	v_or_b32_e32 v0, s38, v3
	v_add_u32_e32 v38, s2, v40
	v_add_u32_e32 v36, s7, v0
	v_ashrrev_i32_e32 v39, 31, v38
	v_ashrrev_i32_e32 v37, 31, v36
	v_lshlrev_b64 v[38:39], 12, v[38:39]
	v_lshlrev_b64 v[36:37], 12, v[36:37]
	v_lshl_add_u64 v[38:39], v[34:35], 0, v[38:39]
	v_lshl_add_u64 v[36:37], v[34:35], 0, v[36:37]
	global_load_dword v244, v[38:39], off
	global_load_dword v245, v[36:37], off
	s_add_i32 s39, s37, 16
	s_add_i32 s38, s30, 16
	v_or_b32_e32 v40, s39, v2
	v_or_b32_e32 v0, s38, v3
	v_add_u32_e32 v38, s2, v40
	v_add_u32_e32 v36, s7, v0
	v_ashrrev_i32_e32 v39, 31, v38
	v_ashrrev_i32_e32 v37, 31, v36
	v_lshlrev_b64 v[38:39], 12, v[38:39]
	v_lshlrev_b64 v[36:37], 12, v[36:37]
	v_lshl_add_u64 v[38:39], v[34:35], 0, v[38:39]
	v_lshl_add_u64 v[36:37], v[34:35], 0, v[36:37]
	global_load_dword v246, v[38:39], off
	global_load_dword v247, v[36:37], off
	s_add_i32 s39, s37, 20
	s_add_i32 s38, s30, 20
	v_or_b32_e32 v40, s39, v2
	v_or_b32_e32 v0, s38, v3
	v_add_u32_e32 v38, s2, v40
	v_add_u32_e32 v36, s7, v0
	v_ashrrev_i32_e32 v39, 31, v38
	v_ashrrev_i32_e32 v37, 31, v36
	v_lshlrev_b64 v[38:39], 12, v[38:39]
	v_lshlrev_b64 v[36:37], 12, v[36:37]
	v_lshl_add_u64 v[38:39], v[34:35], 0, v[38:39]
	v_lshl_add_u64 v[36:37], v[34:35], 0, v[36:37]
	global_load_dword v248, v[38:39], off
	global_load_dword v249, v[36:37], off
	s_add_i32 s39, s37, 24
	s_add_i32 s38, s30, 24
	v_or_b32_e32 v40, s39, v2
	v_or_b32_e32 v0, s38, v3
	v_add_u32_e32 v38, s2, v40
	v_add_u32_e32 v36, s7, v0
	v_ashrrev_i32_e32 v39, 31, v38
	v_ashrrev_i32_e32 v37, 31, v36
	v_lshlrev_b64 v[38:39], 12, v[38:39]
	v_lshlrev_b64 v[36:37], 12, v[36:37]
	v_lshl_add_u64 v[38:39], v[34:35], 0, v[38:39]
	v_lshl_add_u64 v[36:37], v[34:35], 0, v[36:37]
	global_load_dword v250, v[38:39], off
	global_load_dword v251, v[36:37], off
	s_add_i32 s39, s37, 28
	s_add_i32 s38, s30, 28
	v_or_b32_e32 v40, s39, v2
	v_or_b32_e32 v0, s38, v3
	v_add_u32_e32 v38, s2, v40
	v_add_u32_e32 v36, s7, v0
	v_ashrrev_i32_e32 v39, 31, v38
	v_ashrrev_i32_e32 v37, 31, v36
	v_lshlrev_b64 v[38:39], 12, v[38:39]
	v_lshlrev_b64 v[36:37], 12, v[36:37]
	v_lshl_add_u64 v[38:39], v[34:35], 0, v[38:39]
	v_lshl_add_u64 v[36:37], v[34:35], 0, v[36:37]
	global_load_dword v252, v[38:39], off
	global_load_dword v253, v[36:37], off
	s_add_i32 s8, s8, 16
	s_add_i32 s3, s3, 16
	s_add_i32 s9, s9, -16
	v_or_b32_e32 v40, s37, v2
	v_or_b32_e32 v0, s30, v3
	v_mad_u64_u32 v[36:37], s[38:39], v40, s75, v[6:7]
	v_mad_u64_u32 v[38:39], s[38:39], v0, s75, v[6:7]
	s_waitcnt vmcnt(14)
	ds_write_b32 v36, v41
	ds_write_b32 v38, v42
	s_add_i32 s39, s37, 4
	s_add_i32 s38, s30, 4
	v_or_b32_e32 v40, s39, v2
	v_or_b32_e32 v0, s38, v3
	v_mad_u64_u32 v[36:37], s[38:39], v40, s75, v[6:7]
	v_mad_u64_u32 v[38:39], s[38:39], v0, s75, v[6:7]
	s_waitcnt vmcnt(12)
	ds_write_b32 v36, v240
	ds_write_b32 v38, v241
	s_add_i32 s39, s37, 8
	s_add_i32 s38, s30, 8
	v_or_b32_e32 v40, s39, v2
	v_or_b32_e32 v0, s38, v3
	v_mad_u64_u32 v[36:37], s[38:39], v40, s75, v[6:7]
	v_mad_u64_u32 v[38:39], s[38:39], v0, s75, v[6:7]
	s_waitcnt vmcnt(10)
	ds_write_b32 v36, v242
	ds_write_b32 v38, v243
	s_add_i32 s39, s37, 12
	s_add_i32 s38, s30, 12
	v_or_b32_e32 v40, s39, v2
	v_or_b32_e32 v0, s38, v3
	v_mad_u64_u32 v[36:37], s[38:39], v40, s75, v[6:7]
	v_mad_u64_u32 v[38:39], s[38:39], v0, s75, v[6:7]
	s_waitcnt vmcnt(8)
	ds_write_b32 v36, v244
	ds_write_b32 v38, v245
	s_add_i32 s39, s37, 16
	s_add_i32 s38, s30, 16
	v_or_b32_e32 v40, s39, v2
	v_or_b32_e32 v0, s38, v3
	v_mad_u64_u32 v[36:37], s[38:39], v40, s75, v[6:7]
	v_mad_u64_u32 v[38:39], s[38:39], v0, s75, v[6:7]
	s_waitcnt vmcnt(6)
	ds_write_b32 v36, v246
	ds_write_b32 v38, v247
	s_add_i32 s39, s37, 20
	s_add_i32 s38, s30, 20
	v_or_b32_e32 v40, s39, v2
	v_or_b32_e32 v0, s38, v3
	v_mad_u64_u32 v[36:37], s[38:39], v40, s75, v[6:7]
	v_mad_u64_u32 v[38:39], s[38:39], v0, s75, v[6:7]
	s_waitcnt vmcnt(4)
	ds_write_b32 v36, v248
	ds_write_b32 v38, v249
	s_add_i32 s39, s37, 24
	s_add_i32 s38, s30, 24
	v_or_b32_e32 v40, s39, v2
	v_or_b32_e32 v0, s38, v3
	v_mad_u64_u32 v[36:37], s[38:39], v40, s75, v[6:7]
	v_mad_u64_u32 v[38:39], s[38:39], v0, s75, v[6:7]
	s_waitcnt vmcnt(2)
	ds_write_b32 v36, v250
	ds_write_b32 v38, v251
	s_add_i32 s39, s37, 28
	s_add_i32 s38, s30, 28
	v_or_b32_e32 v40, s39, v2
	v_or_b32_e32 v0, s38, v3
	v_mad_u64_u32 v[36:37], s[38:39], v40, s75, v[6:7]
	v_mad_u64_u32 v[38:39], s[38:39], v0, s75, v[6:7]
	s_waitcnt vmcnt(0)
	ds_write_b32 v36, v252
	ds_write_b32 v38, v253
	s_cmp_lg_u32 s9, 0
	s_cbranch_scc1 .LBB0_260
; __device__ __forceinline__ unsigned cvt_pk_bf16(float lo, float hi) { unsigned r; asm volatile("v_cvt_pk_bf16_f32 %0, %1, %2" : "=v"(r) : "v"(lo), "v"(hi)); return r; }
; #define LAS __attribute__((address_space(3)))
; #define LDS_WAIT() asm volatile("s_waitcnt lgkmcnt(0)" ::: "memory")
; __device__ __forceinline__ void tr_item(const float* W, int Nsrc, int k0, int j0, const float* kscale, bf16_t* WT, int Kdst, int R0, LAS float* scr, int lane) {
;     ...
;     const int c = lane & 7;
; #pragma unroll
;     for (int j = 0; j < 4; ++j) { const int n = (lane >> 3) + 8 * j; const LAS float* s = scr + (8 * c) * 33 + n;
;         u32x4 o; o.x = cvt_pk_bf16(s[0 * 33], s[1 * 33]); o.y = cvt_pk_bf16(s[2 * 33], s[3 * 33]); o.z = cvt_pk_bf16(s[4 * 33], s[5 * 33]); o.w = cvt_pk_bf16(s[6 * 33], s[7 * 33]);
;         *(u32x4*)(WT + (size_t)(R0 + n) * Kdst + k0 + 8 * c) = o; }
;     LDS_WAIT();
	s_waitcnt lgkmcnt(0)
	ds_read2_b32 v[34:35], v7 offset1:33
	s_waitcnt lgkmcnt(0)
	v_cvt_pk_bf16_f32 v34, v34, v35
	ds_read2_b32 v[36:37], v7 offset0:66 offset1:99
	s_mov_b32 s3, s31
	s_waitcnt lgkmcnt(0)
	v_cvt_pk_bf16_f32 v35, v36, v37
	ds_read2_b32 v[36:37], v7 offset0:132 offset1:165
	v_or_b32_e32 v0, s6, v5
	v_lshl_add_u64 v[38:39], s[2:3], 1, v[16:17]
	s_waitcnt lgkmcnt(0)
	v_cvt_pk_bf16_f32 v36, v36, v37
	ds_read2_b32 v[40:41], v7 offset0:198 offset1:231
	v_lshlrev_b32_e32 v0, 11, v0
	s_waitcnt lgkmcnt(0)
	v_cvt_pk_bf16_f32 v37, v40, v41
	v_lshl_add_u64 v[40:41], v[38:39], 0, v[0:1]
	global_store_dwordx4 v[40:41], v[34:37], off
	ds_read2_b32 v[34:35], v7 offset0:8 offset1:41
	v_or_b32_e32 v0, s6, v56
	s_waitcnt lgkmcnt(0)
	v_cvt_pk_bf16_f32 v34, v34, v35
	ds_read2_b32 v[36:37], v7 offset0:74 offset1:107
	s_waitcnt lgkmcnt(0)
	v_cvt_pk_bf16_f32 v35, v36, v37
	ds_read2_b32 v[36:37], v7 offset0:140 offset1:173
	s_waitcnt lgkmcnt(0)
	v_cvt_pk_bf16_f32 v36, v36, v37
	ds_read2_b32 v[40:41], v7 offset0:206 offset1:239
	v_lshlrev_b32_e32 v0, 11, v0
	s_waitcnt lgkmcnt(0)
	v_cvt_pk_bf16_f32 v37, v40, v41
	v_lshl_add_u64 v[40:41], v[38:39], 0, v[0:1]
	global_store_dwordx4 v[40:41], v[34:37], off
	ds_read2_b32 v[34:35], v7 offset0:16 offset1:49
	v_or_b32_e32 v0, s6, v57
	s_waitcnt lgkmcnt(0)
	v_cvt_pk_bf16_f32 v34, v34, v35
	ds_read2_b32 v[36:37], v7 offset0:82 offset1:115
	s_waitcnt lgkmcnt(0)
	v_cvt_pk_bf16_f32 v35, v36, v37
	ds_read2_b32 v[36:37], v7 offset0:148 offset1:181
	s_waitcnt lgkmcnt(0)
	v_cvt_pk_bf16_f32 v36, v36, v37
	ds_read2_b32 v[40:41], v7 offset0:214 offset1:247
	v_lshlrev_b32_e32 v0, 11, v0
	s_waitcnt lgkmcnt(0)
	v_cvt_pk_bf16_f32 v37, v40, v41
	v_lshl_add_u64 v[40:41], v[38:39], 0, v[0:1]
	global_store_dwordx4 v[40:41], v[34:37], off
	ds_read2_b32 v[34:35], v7 offset0:24 offset1:57
	v_or_b32_e32 v0, s6, v58
	s_waitcnt lgkmcnt(0)
	v_cvt_pk_bf16_f32 v34, v34, v35
	ds_read2_b32 v[36:37], v7 offset0:90 offset1:123
	v_lshlrev_b32_e32 v0, 11, v0
	s_waitcnt lgkmcnt(0)
	v_cvt_pk_bf16_f32 v35, v36, v37
	ds_read2_b32 v[36:37], v7 offset0:156 offset1:189
	v_lshl_add_u64 v[38:39], v[38:39], 0, v[0:1]
	s_waitcnt lgkmcnt(0)
	v_cvt_pk_bf16_f32 v36, v36, v37
	ds_read2_b32 v[40:41], v7 offset0:222 offset1:255
	s_waitcnt lgkmcnt(0)
	v_cvt_pk_bf16_f32 v37, v40, v41
	global_store_dwordx4 v[38:39], v[34:37], off
	s_waitcnt lgkmcnt(0)

; #define LAS __attribute__((address_space(3)))
; #define LDS_WAIT() asm volatile("s_waitcnt lgkmcnt(0)" ::: "memory")
; __device__ __forceinline__ void tr_item(const float* W, int Nsrc, int k0, int j0, const float* kscale, bf16_t* WT, int Kdst, int R0, LAS float* scr, int lane) {
;     if (j0 >= 0) {
; #pragma unroll 8
;         for (int i = 0; i < 32; ++i) { const int kk = 2 * i + (lane >> 5); float v = W[(size_t)(k0 + kk) * Nsrc + j0 + (lane & 31)]; if (kscale) v *= kscale[k0 + kk]; scr[kk * 33 + (lane & 31)] = v; }
;     } else {
; #pragma unroll 8
;         for (int i = 0; i < 32; ++i) { const int kk = 2 * i + (lane >> 5); scr[kk * 33 + (lane & 31)] = 0.f; }
;     }
;     LDS_WAIT();
.LBB0_327:
	s_lshl_b32 s37, s7, 1
	s_lshl_b32 s30, s6, 1
	v_or_b32_e32 v40, s37, v2
	v_or_b32_e32 v0, s30, v3
	v_add_u32_e32 v36, s2, v40
	v_add_u32_e32 v38, s3, v0
	v_mad_i64_i32 v[36:37], s[38:39], v36, s21, v[34:35]
	v_mad_i64_i32 v[38:39], s[38:39], v38, s21, v[34:35]
	global_load_dword v41, v[36:37], off
	global_load_dword v42, v[38:39], off
	s_add_i32 s39, s37, 4
	s_add_i32 s38, s30, 4
	v_or_b32_e32 v40, s39, v2
	v_or_b32_e32 v0, s38, v3
	v_add_u32_e32 v36, s2, v40
	v_add_u32_e32 v38, s3, v0
	v_mad_i64_i32 v[36:37], s[38:39], v36, s21, v[34:35]
	v_mad_i64_i32 v[38:39], s[38:39], v38, s21, v[34:35]
	global_load_dword v240, v[36:37], off
	global_load_dword v241, v[38:39], off
	s_add_i32 s39, s37, 8
	s_add_i32 s38, s30, 8
	v_or_b32_e32 v40, s39, v2
	v_or_b32_e32 v0, s38, v3
	v_add_u32_e32 v36, s2, v40
	v_add_u32_e32 v38, s3, v0
	v_mad_i64_i32 v[36:37], s[38:39], v36, s21, v[34:35]
	v_mad_i64_i32 v[38:39], s[38:39], v38, s21, v[34:35]
	global_load_dword v242, v[36:37], off
	global_load_dword v243, v[38:39], off
	s_add_i32 s39, s37, 12
	s_add_i32 s38, s30, 12
	v_or_b32_e32 v40, s39, v2
	v_or_b32_e32 v0, s38, v3
	v_add_u32_e32 v36, s2, v40
	v_add_u32_e32 v38, s3, v0
	v_mad_i64_i32 v[36:37], s[38:39], v36, s21, v[34:35]
	v_mad_i64_i32 v[38:39], s[38:39], v38, s21, v[34:35]
	global_load_dword v244, v[36:37], off
	global_load_dword v245, v[38:39], off
	s_add_i32 s39, s37, 16
	s_add_i32 s38, s30, 16
	v_or_b32_e32 v40, s39, v2
	v_or_b32_e32 v0, s38, v3
	v_add_u32_e32 v36, s2, v40
	v_add_u32_e32 v38, s3, v0
	v_mad_i64_i32 v[36:37], s[38:39], v36, s21, v[34:35]
	v_mad_i64_i32 v[38:39], s[38:39], v38, s21, v[34:35]
	global_load_dword v246, v[36:37], off
	global_load_dword v247, v[38:39], off
	s_add_i32 s39, s37, 20
	s_add_i32 s38, s30, 20
	v_or_b32_e32 v40, s39, v2
	v_or_b32_e32 v0, s38, v3
	v_add_u32_e32 v36, s2, v40
	v_add_u32_e32 v38, s3, v0
	v_mad_i64_i32 v[36:37], s[38:39], v36, s21, v[34:35]
	v_mad_i64_i32 v[38:39], s[38:39], v38, s21, v[34:35]
	global_load_dword v248, v[36:37], off
	global_load_dword v249, v[38:39], off
	s_add_i32 s39, s37, 24
	s_add_i32 s38, s30, 24
	v_or_b32_e32 v40, s39, v2
	v_or_b32_e32 v0, s38, v3
	v_add_u32_e32 v36, s2, v40
	v_add_u32_e32 v38, s3, v0
	v_mad_i64_i32 v[36:37], s[38:39], v36, s21, v[34:35]
	v_mad_i64_i32 v[38:39], s[38:39], v38, s21, v[34:35]
	global_load_dword v250, v[36:37], off
	global_load_dword v251, v[38:39], off
	s_add_i32 s39, s37, 28
	s_add_i32 s38, s30, 28
	v_or_b32_e32 v40, s39, v2
	v_or_b32_e32 v0, s38, v3
	v_add_u32_e32 v36, s2, v40
	v_add_u32_e32 v38, s3, v0
	v_mad_i64_i32 v[36:37], s[38:39], v36, s21, v[34:35]
	v_mad_i64_i32 v[38:39], s[38:39], v38, s21, v[34:35]
	global_load_dword v252, v[36:37], off
	global_load_dword v253, v[38:39], off
	s_add_i32 s7, s7, 16
	s_add_i32 s6, s6, 16
	s_add_i32 s9, s9, -16
	v_or_b32_e32 v40, s37, v2
	v_or_b32_e32 v0, s30, v3
	v_mad_u64_u32 v[36:37], s[38:39], v40, s75, v[6:7]
	v_mad_u64_u32 v[38:39], s[38:39], v0, s75, v[6:7]
	s_waitcnt vmcnt(14)
	ds_write_b32 v36, v41
	ds_write_b32 v38, v42
	s_add_i32 s39, s37, 4
	s_add_i32 s38, s30, 4
	v_or_b32_e32 v40, s39, v2
	v_or_b32_e32 v0, s38, v3
	v_mad_u64_u32 v[36:37], s[38:39], v40, s75, v[6:7]
	v_mad_u64_u32 v[38:39], s[38:39], v0, s75, v[6:7]
	s_waitcnt vmcnt(12)
	ds_write_b32 v36, v240
	ds_write_b32 v38, v241
	s_add_i32 s39, s37, 8
	s_add_i32 s38, s30, 8
	v_or_b32_e32 v40, s39, v2
	v_or_b32_e32 v0, s38, v3
	v_mad_u64_u32 v[36:37], s[38:39], v40, s75, v[6:7]
	v_mad_u64_u32 v[38:39], s[38:39], v0, s75, v[6:7]
	s_waitcnt vmcnt(10)
	ds_write_b32 v36, v242
	ds_write_b32 v38, v243
	s_add_i32 s39, s37, 12
	s_add_i32 s38, s30, 12
	v_or_b32_e32 v40, s39, v2
	v_or_b32_e32 v0, s38, v3
	v_mad_u64_u32 v[36:37], s[38:39], v40, s75, v[6:7]
	v_mad_u64_u32 v[38:39], s[38:39], v0, s75, v[6:7]
	s_waitcnt vmcnt(8)
	ds_write_b32 v36, v244
	ds_write_b32 v38, v245
	s_add_i32 s39, s37, 16
	s_add_i32 s38, s30, 16
	v_or_b32_e32 v40, s39, v2
	v_or_b32_e32 v0, s38, v3
	v_mad_u64_u32 v[36:37], s[38:39], v40, s75, v[6:7]
	v_mad_u64_u32 v[38:39], s[38:39], v0, s75, v[6:7]
	s_waitcnt vmcnt(6)
	ds_write_b32 v36, v246
	ds_write_b32 v38, v247
	s_add_i32 s39, s37, 20
	s_add_i32 s38, s30, 20
	v_or_b32_e32 v40, s39, v2
	v_or_b32_e32 v0, s38, v3
	v_mad_u64_u32 v[36:37], s[38:39], v40, s75, v[6:7]
	v_mad_u64_u32 v[38:39], s[38:39], v0, s75, v[6:7]
	s_waitcnt vmcnt(4)
	ds_write_b32 v36, v248
	ds_write_b32 v38, v249
	s_add_i32 s39, s37, 24
	s_add_i32 s38, s30, 24
	v_or_b32_e32 v40, s39, v2
	v_or_b32_e32 v0, s38, v3
	v_mad_u64_u32 v[36:37], s[38:39], v40, s75, v[6:7]
	v_mad_u64_u32 v[38:39], s[38:39], v0, s75, v[6:7]
	s_waitcnt vmcnt(2)
	ds_write_b32 v36, v250
	ds_write_b32 v38, v251
	s_add_i32 s39, s37, 28
	s_add_i32 s38, s30, 28
	v_or_b32_e32 v40, s39, v2
	v_or_b32_e32 v0, s38, v3
	v_mad_u64_u32 v[36:37], s[38:39], v40, s75, v[6:7]
	v_mad_u64_u32 v[38:39], s[38:39], v0, s75, v[6:7]
	s_waitcnt vmcnt(0)
	ds_write_b32 v36, v252
	ds_write_b32 v38, v253
	s_cmp_eq_u32 s9, 0
	s_cbranch_scc0 .LBB0_327
	s_branch .LBB0_231
